# P2 sample task: the 8 new-token V ushort loads batched behind one wait (were 4 dependent round trips)
# speedup vs baseline: 1.0121x; 1.0005x over previous
.LBB0_731:
	s_andn2_b64 vcc, exec, s[12:13]
	s_cbranch_vccnz .LBB0_722
	s_add_i32 s13, s14, s33
	s_and_b32 s14, s13, 3
	s_ashr_i32 s12, s13, 2
	s_and_b32 s13, s13, -4
	s_add_i32 s94, s13, 0x2000
	v_or_b32_e32 v96, s94, v125
	v_ashrrev_i32_e32 v97, 31, v96
	v_readlane_b32 s24, v254, 54
	v_lshl_or_b32 v103, s14, 3, v156
	v_lshlrev_b64 v[100:101], 12, v[96:97]
	v_readlane_b32 s25, v254, 55
	v_lshlrev_b32_e32 v130, 7, v103
	v_mov_b32_e32 v93, v131
	v_lshl_add_u64 v[0:1], s[24:25], 0, v[100:101]
	v_lshl_add_u64 v[0:1], v[0:1], 0, v[130:131]
	v_lshl_add_u64 v[0:1], v[0:1], 0, v[92:93]
	s_lshl_b32 s24, s14, 8
	s_mov_b32 s25, s92
	v_or_b32_e32 v182, s94, v136
	global_load_dwordx4 v[64:67], v[0:1], off
	global_load_dwordx4 v[88:91], v[0:1], off offset:32
	global_load_dwordx4 v[84:87], v[0:1], off offset:64
	global_load_dwordx4 v[80:83], v[0:1], off offset:96
	v_lshl_add_u64 v[152:153], v[140:141], 0, s[24:25]
	v_ashrrev_i32_e32 v183, 31, v182
	v_readlane_b32 s24, v254, 56
	s_lshl_b32 s13, s12, 7
	v_lshlrev_b64 v[182:183], 9, v[182:183]
	v_readlane_b32 s25, v254, 57
	v_or_b32_e32 v208, s13, v136
	v_ashrrev_i32_e32 v209, 31, v208
	v_lshl_add_u64 v[182:183], s[24:25], 0, v[182:183]
	s_lshl_b32 s24, s14, 7
	s_mov_b32 s25, s92
	v_lshl_add_u64 v[182:183], v[182:183], 0, s[24:25]
	v_lshl_add_u64 v[98:99], v[182:183], 0, v[92:93]
	v_lshlrev_b64 v[208:209], 10, v[208:209]
	s_mov_b64 s[60:61], 0x8000
	v_lshl_add_u64 v[182:183], v[152:153], 0, v[208:209]
	v_lshl_add_u64 v[208:209], v[182:183], 0, s[60:61]
	v_lshl_add_u64 v[222:223], v[208:209], 0, s[60:61]
	v_lshl_add_u64 v[252:253], v[222:223], 0, s[60:61]
	global_load_dwordx4 v[104:107], v[182:183], off nt
	global_load_dwordx4 v[108:111], v[182:183], off offset:16 nt
	global_load_dwordx4 v[112:115], v[182:183], off offset:64 nt
	global_load_dwordx4 v[116:119], v[182:183], off offset:80 nt
	global_load_dwordx4 v[120:123], v[182:183], off offset:128 nt
	global_load_dwordx4 v[144:147], v[182:183], off offset:144 nt
	global_load_dwordx4 v[148:151], v[182:183], off offset:192 nt
	global_load_dwordx4 v[184:187], v[182:183], off offset:208 nt
	global_load_dwordx4 v[188:191], v[208:209], off nt
	global_load_dwordx4 v[192:195], v[208:209], off offset:16 nt
	global_load_dwordx4 v[196:199], v[208:209], off offset:64 nt
	global_load_dwordx4 v[200:203], v[208:209], off offset:80 nt
	global_load_dwordx4 v[204:207], v[208:209], off offset:128 nt
	global_load_dwordx4 v[224:227], v[208:209], off offset:144 nt
	global_load_dwordx4 v[228:231], v[208:209], off offset:192 nt
	global_load_dwordx4 v[232:235], v[208:209], off offset:208 nt
	global_load_dwordx4 v[236:239], v[222:223], off nt
	global_load_dwordx4 v[240:243], v[222:223], off offset:16 nt
	global_load_dwordx4 v[244:247], v[222:223], off offset:64 nt
	global_load_dwordx4 v[248:251], v[222:223], off offset:80 nt
	global_load_dwordx4 v[0:3], v[222:223], off offset:128 nt
	global_load_dwordx4 v[4:7], v[222:223], off offset:144 nt
	global_load_dwordx4 v[8:11], v[222:223], off offset:192 nt
	global_load_dwordx4 v[12:15], v[222:223], off offset:208 nt
	v_mov_b32_e32 v92, 0
	s_waitcnt vmcnt(16)
	v_cvt_pk_bf16_f32 v104, v104, v105
	v_cvt_pk_bf16_f32 v105, v106, v107
	v_cvt_pk_bf16_f32 v106, v108, v109
	v_cvt_pk_bf16_f32 v107, v110, v111
	v_cvt_pk_bf16_f32 v112, v112, v113
	v_cvt_pk_bf16_f32 v113, v114, v115
	v_cvt_pk_bf16_f32 v114, v116, v117
	v_cvt_pk_bf16_f32 v115, v118, v119
	v_cvt_pk_bf16_f32 v120, v120, v121
	v_cvt_pk_bf16_f32 v121, v122, v123
	v_cvt_pk_bf16_f32 v122, v144, v145
	v_cvt_pk_bf16_f32 v123, v146, v147
	v_cvt_pk_bf16_f32 v148, v148, v149
	v_cvt_pk_bf16_f32 v149, v150, v151
	v_cvt_pk_bf16_f32 v150, v184, v185
	v_cvt_pk_bf16_f32 v151, v186, v187
	s_nop 1
	v_mfma_f32_32x32x16_bf16 v[16:31], v[104:107], v[64:67], 0
	v_mfma_f32_32x32x16_bf16 v[16:31], v[112:115], v[88:91], v[16:31]
	v_mfma_f32_32x32x16_bf16 v[16:31], v[120:123], v[84:87], v[16:31]
	v_mfma_f32_32x32x16_bf16 v[16:31], v[148:151], v[80:83], v[16:31]
	global_load_dwordx4 v[104:107], v[252:253], off nt
	global_load_dwordx4 v[108:111], v[252:253], off offset:16 nt
	global_load_dwordx4 v[112:115], v[252:253], off offset:64 nt
	global_load_dwordx4 v[116:119], v[252:253], off offset:80 nt
	global_load_dwordx4 v[120:123], v[252:253], off offset:128 nt
	global_load_dwordx4 v[144:147], v[252:253], off offset:144 nt
	global_load_dwordx4 v[148:151], v[252:253], off offset:192 nt
	global_load_dwordx4 v[184:187], v[252:253], off offset:208 nt
	s_waitcnt vmcnt(16)
	v_cvt_pk_bf16_f32 v188, v188, v189
	v_cvt_pk_bf16_f32 v189, v190, v191
	v_cvt_pk_bf16_f32 v190, v192, v193
	v_cvt_pk_bf16_f32 v191, v194, v195
	v_cvt_pk_bf16_f32 v196, v196, v197
	v_cvt_pk_bf16_f32 v197, v198, v199
	v_cvt_pk_bf16_f32 v198, v200, v201
	v_cvt_pk_bf16_f32 v199, v202, v203
	v_cvt_pk_bf16_f32 v204, v204, v205
	v_cvt_pk_bf16_f32 v205, v206, v207
	v_cvt_pk_bf16_f32 v206, v224, v225
	v_cvt_pk_bf16_f32 v207, v226, v227
	v_cvt_pk_bf16_f32 v228, v228, v229
	v_cvt_pk_bf16_f32 v229, v230, v231
	v_cvt_pk_bf16_f32 v230, v232, v233
	v_cvt_pk_bf16_f32 v231, v234, v235
	s_nop 1
	v_mfma_f32_32x32x16_bf16 v[32:47], v[188:191], v[64:67], 0
	v_mfma_f32_32x32x16_bf16 v[32:47], v[196:199], v[88:91], v[32:47]
	v_mfma_f32_32x32x16_bf16 v[32:47], v[204:207], v[84:87], v[32:47]
	v_mfma_f32_32x32x16_bf16 v[32:47], v[228:231], v[80:83], v[32:47]
	v_mov_b32_e32 v188, 0
	v_mov_b32_e32 v189, 0
	v_mov_b32_e32 v190, 0
	v_mov_b32_e32 v191, 0
	v_mov_b32_e32 v192, 0
	v_mov_b32_e32 v193, 0
	v_mov_b32_e32 v194, 0
	v_mov_b32_e32 v195, 0
	v_mov_b32_e32 v196, 0
	v_mov_b32_e32 v197, 0
	v_mov_b32_e32 v198, 0
	v_mov_b32_e32 v199, 0
	v_mov_b32_e32 v200, 0
	v_mov_b32_e32 v201, 0
	v_mov_b32_e32 v202, 0
	v_mov_b32_e32 v203, 0
	s_and_saveexec_b64 vcc, s[42:43]
	global_load_dwordx4 v[188:191], v[98:99], off
	global_load_dwordx4 v[192:195], v[98:99], off offset:32
	global_load_dwordx4 v[196:199], v[98:99], off offset:64
	global_load_dwordx4 v[200:203], v[98:99], off offset:96
	s_or_b64 exec, exec, vcc
	s_waitcnt vmcnt(12)
	v_cvt_pk_bf16_f32 v236, v236, v237
	v_cvt_pk_bf16_f32 v237, v238, v239
	v_cvt_pk_bf16_f32 v238, v240, v241
	v_cvt_pk_bf16_f32 v239, v242, v243
	v_cvt_pk_bf16_f32 v244, v244, v245
	v_cvt_pk_bf16_f32 v245, v246, v247
	v_cvt_pk_bf16_f32 v246, v248, v249
	v_cvt_pk_bf16_f32 v247, v250, v251
	v_cvt_pk_bf16_f32 v0, v0, v1
	v_cvt_pk_bf16_f32 v1, v2, v3
	v_cvt_pk_bf16_f32 v2, v4, v5
	v_cvt_pk_bf16_f32 v3, v6, v7
	v_cvt_pk_bf16_f32 v8, v8, v9
	v_cvt_pk_bf16_f32 v9, v10, v11
	v_cvt_pk_bf16_f32 v10, v12, v13
	v_cvt_pk_bf16_f32 v11, v14, v15
	s_nop 1
	v_mfma_f32_32x32x16_bf16 v[48:63], v[236:239], v[64:67], 0
	v_mfma_f32_32x32x16_bf16 v[48:63], v[244:247], v[88:91], v[48:63]
	v_mfma_f32_32x32x16_bf16 v[48:63], v[0:3], v[84:87], v[48:63]
	v_mfma_f32_32x32x16_bf16 v[48:63], v[8:11], v[80:83], v[48:63]
	s_waitcnt vmcnt(4)
	v_cvt_pk_bf16_f32 v104, v104, v105
	v_cvt_pk_bf16_f32 v105, v106, v107
	v_cvt_pk_bf16_f32 v106, v108, v109
	v_cvt_pk_bf16_f32 v107, v110, v111
	v_cvt_pk_bf16_f32 v112, v112, v113
	v_cvt_pk_bf16_f32 v113, v114, v115
	v_cvt_pk_bf16_f32 v114, v116, v117
	v_cvt_pk_bf16_f32 v115, v118, v119
	v_cvt_pk_bf16_f32 v120, v120, v121
	v_cvt_pk_bf16_f32 v121, v122, v123
	v_cvt_pk_bf16_f32 v122, v144, v145
	v_cvt_pk_bf16_f32 v123, v146, v147
	v_cvt_pk_bf16_f32 v148, v148, v149
	v_cvt_pk_bf16_f32 v149, v150, v151
	v_cvt_pk_bf16_f32 v150, v184, v185
	v_cvt_pk_bf16_f32 v151, v186, v187
	s_nop 1
	v_mfma_f32_32x32x16_bf16 v[0:15], v[104:107], v[64:67], 0
	v_mfma_f32_32x32x16_bf16 v[0:15], v[112:115], v[88:91], v[0:15]
	v_mfma_f32_32x32x16_bf16 v[0:15], v[120:123], v[84:87], v[0:15]
	v_mfma_f32_32x32x16_bf16 v[0:15], v[148:151], v[80:83], v[0:15]
	s_lshl_b32 s14, s14, 6
	v_readlane_b32 s56, v254, 22
	v_readlane_b32 s58, v254, 24
	v_readlane_b32 s59, v254, 25
	s_waitcnt vmcnt(0)
	v_mfma_f32_32x32x16_bf16 v[64:79], v[188:191], v[64:67], 0
	v_mfma_f32_32x32x16_bf16 v[64:79], v[192:195], v[88:91], v[64:79]
	v_mfma_f32_32x32x16_bf16 v[64:79], v[196:199], v[84:87], v[64:79]
	v_lshlrev_b32_e32 v84, 2, v103
	v_mfma_f32_32x32x16_bf16 v[64:79], v[200:203], v[80:83], v[64:79]


	v_cndmask_b32_e64 v18, v179, v18, s[48:49]
	v_cndmask_b32_e64 v19, v19, v179, s[50:51]
	v_readlane_b32 s57, v254, 23
	v_readlane_b32 s60, v254, 26
	global_load_dword v84, v84, s[58:59] nt
	s_nop 6
	v_cndmask_b32_e64 v69, v179, v16, s[44:45]
	v_cndmask_b32_e64 v70, v17, v179, s[46:47]
	v_and_b32_e32 v17, 64, v102
	v_xor_b32_e32 v16, 32, v102
	v_max_f32_e32 v68, v69, v69
	v_add_u32_e32 v17, 64, v17
	v_max_f32_e32 v68, 0xf149f2ca, v68
	v_cmp_lt_i32_e32 vcc, v16, v17
	v_max3_f32 v17, v68, v70, v18
	v_cndmask_b32_e64 v77, v66, v179, s[48:49]
	v_cndmask_b32_e32 v16, v102, v16, vcc
	v_lshlrev_b32_e32 v68, 2, v16
	v_max3_f32 v16, v17, v19, v20
	v_max3_f32 v16, v16, v21, v22
	v_max3_f32 v16, v16, v23, v24
	v_max3_f32 v16, v16, v25, v26
	v_max3_f32 v71, v16, v27, v28
	v_cndmask_b32_e64 v17, v64, v179, s[44:45]
	v_max3_f32 v64, v71, v29, v30
	v_max3_f32 v64, v64, v31, v32
	v_max3_f32 v64, v64, v33, v34
	v_max3_f32 v64, v64, v35, v36
	v_max3_f32 v64, v64, v37, v38
	v_max3_f32 v64, v64, v39, v40
	v_max3_f32 v64, v64, v41, v42
	v_max3_f32 v64, v64, v43, v44
	v_max3_f32 v64, v64, v45, v46
	v_max3_f32 v64, v64, v47, v48
	v_max3_f32 v64, v64, v49, v50
	v_max3_f32 v64, v64, v51, v52
	v_max3_f32 v64, v64, v53, v54
	v_max3_f32 v64, v64, v55, v56
	v_max3_f32 v64, v64, v57, v58
	v_max3_f32 v64, v64, v59, v60
	v_max3_f32 v64, v64, v61, v62
	v_max3_f32 v64, v64, v63, v0
	v_max3_f32 v64, v64, v1, v2
	v_max3_f32 v64, v64, v3, v4
	v_max3_f32 v64, v64, v5, v6
	v_max3_f32 v64, v64, v7, v8
	v_max3_f32 v64, v64, v9, v10
	v_max3_f32 v64, v64, v11, v12
	v_max3_f32 v64, v64, v13, v14
	v_cndmask_b32_e64 v16, v179, v65, s[46:47]
	v_max3_f32 v64, v64, v15, v17
	v_cndmask_b32_e64 v76, v179, v67, s[50:51]
	v_max3_f32 v64, v64, v16, v77
	v_max3_f32 v64, v64, v76, s17
	ds_bpermute_b32 v65, v68, v64
	v_readlane_b32 s61, v254, 27
	v_readlane_b32 s62, v254, 28
	v_readlane_b32 s63, v254, 29
	v_readlane_b32 s64, v254, 30
	s_waitcnt lgkmcnt(0)
	v_max_f32_e32 v65, v65, v65
	v_max_f32_e32 v64, v64, v65
	v_mul_f32_e32 v64, 0x3e38aa3b, v64
	v_readlane_b32 s65, v254, 31
	v_readlane_b32 s66, v254, 32
	v_readlane_b32 s67, v254, 33
	v_readlane_b32 s68, v254, 34
	v_readlane_b32 s69, v254, 35
	v_readlane_b32 s70, v254, 36
	v_readlane_b32 s71, v254, 37
	v_readlane_b32 s56, v254, 6
	v_readlane_b32 s62, v254, 12
	v_readlane_b32 s63, v254, 13
	v_lshlrev_b32_e32 v130, 2, v136
	v_readlane_b32 s57, v254, 7
	v_readlane_b32 s56, v254, 58
	v_readlane_b32 s57, v254, 59
	v_readlane_b32 s58, v254, 8
	v_readlane_b32 s59, v254, 9
	v_readlane_b32 s60, v254, 10
	v_readlane_b32 s61, v254, 11
	v_readlane_b32 s64, v254, 14
	v_readlane_b32 s65, v254, 15
	v_readlane_b32 s66, v254, 16
	v_readlane_b32 s67, v254, 17
	v_readlane_b32 s68, v254, 18
	s_waitcnt vmcnt(0)
	v_mul_f32_e32 v155, 0x3fb8aa3b, v84
	v_max_f32_e32 v181, v64, v155
	v_fma_f32 v64, v69, s18, -v181
	v_fma_f32 v65, v70, s18, -v181
	v_fma_f32 v66, v18, s18, -v181
	v_exp_f32_e32 v18, v64
	v_fma_f32 v67, v19, s18, -v181
	v_exp_f32_e32 v19, v65
	v_fma_f32 v69, v20, s18, -v181
	v_exp_f32_e32 v20, v66
	v_fma_f32 v70, v21, s18, -v181
	v_fma_f32 v26, v26, s18, -v181
	v_exp_f32_e32 v21, v67
	v_fma_f32 v71, v22, s18, -v181
	v_exp_f32_e32 v22, v69
	v_exp_f32_e32 v80, v26
	v_add_f32_e32 v26, 0, v18
	v_fma_f32 v72, v23, s18, -v181
	v_exp_f32_e32 v23, v70
	v_add_f32_e32 v26, v19, v26
	v_fma_f32 v73, v24, s18, -v181
	v_exp_f32_e32 v24, v71
	v_add_f32_e32 v26, v20, v26
	v_fma_f32 v74, v25, s18, -v181
	v_exp_f32_e32 v25, v72
	v_add_f32_e32 v26, v21, v26
	v_exp_f32_e32 v78, v73
	v_add_f32_e32 v26, v22, v26
	v_exp_f32_e32 v79, v74
	v_add_f32_e32 v26, v23, v26
	v_fma_f32 v27, v27, s18, -v181
	v_add_f32_e32 v26, v24, v26
	v_fma_f32 v28, v28, s18, -v181
	v_exp_f32_e32 v81, v27
	v_add_f32_e32 v26, v25, v26
	v_fma_f32 v29, v29, s18, -v181
	v_exp_f32_e32 v82, v28
	v_add_f32_e32 v26, v78, v26
	v_fma_f32 v30, v30, s18, -v181
	v_exp_f32_e32 v83, v29
	v_add_f32_e32 v26, v79, v26
	v_add_f32_e32 v26, v80, v26
	v_exp_f32_e32 v86, v30
	v_fma_f32 v27, v31, s18, -v181
	v_add_f32_e32 v26, v81, v26
	v_exp_f32_e32 v88, v27
	v_fma_f32 v27, v32, s18, -v181
	v_add_f32_e32 v26, v82, v26
	v_exp_f32_e32 v32, v27
	v_fma_f32 v27, v33, s18, -v181
	v_add_f32_e32 v26, v83, v26
	v_exp_f32_e32 v84, v27
	v_fma_f32 v27, v34, s18, -v181
	v_add_f32_e32 v26, v86, v26
	v_exp_f32_e32 v85, v27
	v_fma_f32 v27, v35, s18, -v181
	v_add_f32_e32 v26, v88, v26
	v_exp_f32_e32 v87, v27
	v_fma_f32 v27, v36, s18, -v181
	v_add_f32_e32 v26, v32, v26
	v_exp_f32_e32 v36, v27
	v_fma_f32 v27, v37, s18, -v181
	v_add_f32_e32 v26, v84, v26
	v_exp_f32_e32 v89, v27
	v_fma_f32 v27, v38, s18, -v181
	v_add_f32_e32 v26, v85, v26
	v_exp_f32_e32 v38, v27
	v_fma_f32 v27, v39, s18, -v181
	v_add_f32_e32 v26, v87, v26
	v_exp_f32_e32 v90, v27
	v_fma_f32 v27, v40, s18, -v181
	v_add_f32_e32 v26, v36, v26
	v_exp_f32_e32 v37, v27
	v_fma_f32 v27, v41, s18, -v181
	v_add_f32_e32 v26, v89, v26
	v_exp_f32_e32 v39, v27
	v_fma_f32 v27, v42, s18, -v181
	v_add_f32_e32 v26, v38, v26
	v_exp_f32_e32 v33, v27
	v_fma_f32 v27, v43, s18, -v181
	v_add_f32_e32 v26, v90, v26
	v_exp_f32_e32 v64, v27
	v_fma_f32 v27, v44, s18, -v181
	v_add_f32_e32 v26, v37, v26
	v_exp_f32_e32 v65, v27
	v_fma_f32 v27, v45, s18, -v181
	v_add_f32_e32 v26, v39, v26
	v_exp_f32_e32 v66, v27
	v_fma_f32 v27, v46, s18, -v181
	v_add_f32_e32 v26, v33, v26
	v_exp_f32_e32 v67, v27
	v_fma_f32 v27, v47, s18, -v181
	v_add_f32_e32 v26, v64, v26
	v_exp_f32_e32 v69, v27
	v_fma_f32 v27, v48, s18, -v181
	v_add_f32_e32 v26, v65, v26
	v_exp_f32_e32 v44, v27
	v_fma_f32 v27, v49, s18, -v181
	v_add_f32_e32 v26, v66, v26
	v_exp_f32_e32 v45, v27
	v_fma_f32 v27, v50, s18, -v181
	v_add_f32_e32 v26, v67, v26
	v_exp_f32_e32 v46, v27
	v_fma_f32 v27, v51, s18, -v181
	v_add_f32_e32 v26, v69, v26
	v_exp_f32_e32 v47, v27
	v_fma_f32 v27, v52, s18, -v181
	v_add_f32_e32 v26, v44, v26
	v_exp_f32_e32 v49, v27
	v_fma_f32 v27, v53, s18, -v181
	v_add_f32_e32 v26, v45, v26
	v_exp_f32_e32 v51, v27
	v_fma_f32 v27, v54, s18, -v181
	v_add_f32_e32 v26, v46, v26
	v_exp_f32_e32 v53, v27
	v_fma_f32 v27, v55, s18, -v181
	v_add_f32_e32 v26, v47, v26
	v_exp_f32_e32 v55, v27
	v_fma_f32 v27, v56, s18, -v181
	v_add_f32_e32 v26, v49, v26
	v_exp_f32_e32 v48, v27
	v_fma_f32 v27, v57, s18, -v181
	v_add_f32_e32 v26, v51, v26
	v_exp_f32_e32 v50, v27
	v_fma_f32 v27, v58, s18, -v181
	v_add_f32_e32 v26, v53, v26
	v_exp_f32_e32 v52, v27
	v_fma_f32 v27, v59, s18, -v181
	v_add_f32_e32 v26, v55, v26
	v_exp_f32_e32 v54, v27
	v_fma_f32 v27, v60, s18, -v181
	v_add_f32_e32 v26, v48, v26
	v_exp_f32_e32 v57, v27
	v_fma_f32 v27, v61, s18, -v181
	v_add_f32_e32 v26, v50, v26
	v_exp_f32_e32 v59, v27
	v_fma_f32 v27, v62, s18, -v181
	v_add_f32_e32 v26, v52, v26
	v_exp_f32_e32 v61, v27
	v_fma_f32 v27, v63, s18, -v181
	v_add_f32_e32 v26, v54, v26
	v_exp_f32_e32 v70, v27
	v_fma_f32 v0, v0, s18, -v181
	v_add_f32_e32 v26, v57, v26
	v_exp_f32_e32 v56, v0
	v_fma_f32 v1, v1, s18, -v181
	v_add_f32_e32 v0, v59, v26
	v_exp_f32_e32 v58, v1
	v_fma_f32 v1, v2, s18, -v181
	v_add_f32_e32 v0, v61, v0
	v_exp_f32_e32 v60, v1
	v_fma_f32 v1, v3, s18, -v181
	v_add_f32_e32 v0, v70, v0
	v_exp_f32_e32 v63, v1
	v_fma_f32 v1, v4, s18, -v181
	v_add_f32_e32 v0, v56, v0
	v_exp_f32_e32 v71, v1
	v_fma_f32 v1, v5, s18, -v181
	v_add_f32_e32 v0, v58, v0
	v_exp_f32_e32 v73, v1
	v_fma_f32 v1, v6, s18, -v181
	v_add_f32_e32 v0, v60, v0
	v_exp_f32_e32 v74, v1
	v_fma_f32 v1, v7, s18, -v181
	v_add_f32_e32 v0, v63, v0
	v_exp_f32_e32 v75, v1
	v_fma_f32 v1, v8, s18, -v181
	v_add_f32_e32 v0, v71, v0
	v_exp_f32_e32 v62, v1
	v_add_f32_e32 v0, v73, v0
	v_add_f32_e32 v0, v74, v0
	v_or_b32_e32 v34, s13, v137
	s_lshl_b32 s13, s14, 2
	v_add_f32_e32 v0, v75, v0
	s_add_u32 vcc_lo, s62, s13
	v_add_f32_e32 v91, v62, v0
	v_fma_f32 v0, v9, s18, -v181
	s_addc_u32 vcc_hi, s63, 0
	v_ashrrev_i32_e32 v35, 31, v34
	v_or_b32_e32 v4, 1, v34
	v_or_b32_e32 v8, 2, v34
	v_or_b32_e32 v28, 3, v34
	v_or_b32_e32 v42, 8, v34
	v_or_b32_e32 v94, 9, v34
	v_or_b32_e32 v104, 10, v34
	v_or_b32_e32 v108, 11, v34
	v_exp_f32_e32 v72, v0
	v_lshl_add_u64 v[40:41], vcc, 0, v[130:131]
	v_lshlrev_b64 v[0:1], 10, v[34:35]
	v_ashrrev_i32_e32 v5, 31, v4
	v_ashrrev_i32_e32 v9, 31, v8
	v_ashrrev_i32_e32 v29, 31, v28
	v_ashrrev_i32_e32 v43, 31, v42
	v_ashrrev_i32_e32 v95, 31, v94
	v_ashrrev_i32_e32 v105, 31, v104
	v_ashrrev_i32_e32 v109, 31, v108
	v_lshl_add_u64 v[2:3], v[40:41], 0, v[0:1]
	v_lshlrev_b64 v[4:5], 10, v[4:5]
	v_lshlrev_b64 v[8:9], 10, v[8:9]
	v_lshlrev_b64 v[28:29], 10, v[28:29]
	v_lshlrev_b64 v[92:93], 10, v[42:43]
	v_lshlrev_b64 v[94:95], 10, v[94:95]
	v_lshlrev_b64 v[104:105], 10, v[104:105]
	v_lshlrev_b64 v[108:109], 10, v[108:109]
	v_lshl_add_u64 v[6:7], v[40:41], 0, v[4:5]
	v_lshl_add_u64 v[26:27], v[40:41], 0, v[8:9]
	v_lshl_add_u64 v[30:31], v[40:41], 0, v[28:29]
	v_lshl_add_u64 v[42:43], v[40:41], 0, v[92:93]
	v_lshl_add_u64 v[98:99], v[40:41], 0, v[94:95]
	v_lshl_add_u64 v[106:107], v[40:41], 0, v[104:105]
	v_lshl_add_u64 v[110:111], v[40:41], 0, v[108:109]
	global_load_dword v35, v[2:3], off nt
	global_load_dword v143, v[6:7], off nt
	global_load_dword v144, v[26:27], off nt
	global_load_dword v145, v[30:31], off nt
	global_load_dword v146, v[42:43], off nt
	global_load_dword v147, v[98:99], off nt
	global_load_dword v148, v[106:107], off nt
	global_load_dword v149, v[110:111], off nt
	v_lshlrev_b32_e32 v130, 2, v124
	v_lshl_add_u64 v[42:43], vcc, 0, v[130:131]
	v_lshl_add_u64 v[0:1], v[42:43], 0, v[0:1]
	v_lshl_add_u64 v[2:3], v[42:43], 0, v[4:5]
	v_lshl_add_u64 v[4:5], v[42:43], 0, v[8:9]
	v_lshl_add_u64 v[6:7], v[42:43], 0, v[28:29]
	v_lshl_add_u64 v[8:9], v[42:43], 0, v[92:93]
	v_lshl_add_u64 v[26:27], v[42:43], 0, v[94:95]
	v_lshl_add_u64 v[28:29], v[42:43], 0, v[104:105]
	v_lshl_add_u64 v[30:31], v[42:43], 0, v[108:109]
	global_load_dword v130, v[0:1], off nt
	global_load_dword v150, v[2:3], off nt
	global_load_dword v151, v[4:5], off nt
	global_load_dword v152, v[6:7], off nt
	global_load_dword v153, v[8:9], off nt
	global_load_dword v182, v[26:27], off nt
	global_load_dword v183, v[28:29], off nt
	global_load_dword v184, v[30:31], off nt
	v_or_b32_e32 v0, 16, v34
	v_ashrrev_i32_e32 v1, 31, v0
	v_or_b32_e32 v4, 17, v34
	v_or_b32_e32 v8, 18, v34
	v_or_b32_e32 v28, 19, v34
	v_or_b32_e32 v92, 24, v34
	v_or_b32_e32 v98, 25, v34
	v_or_b32_e32 v106, 26, v34
	v_or_b32_e32 v110, 27, v34
	v_lshlrev_b64 v[0:1], 10, v[0:1]
	v_ashrrev_i32_e32 v5, 31, v4
	v_ashrrev_i32_e32 v9, 31, v8
	v_ashrrev_i32_e32 v29, 31, v28
	v_ashrrev_i32_e32 v93, 31, v92
	v_ashrrev_i32_e32 v99, 31, v98
	v_ashrrev_i32_e32 v107, 31, v106
	v_ashrrev_i32_e32 v111, 31, v110
	v_lshl_add_u64 v[2:3], v[40:41], 0, v[0:1]
	v_lshlrev_b64 v[4:5], 10, v[4:5]
	v_lshlrev_b64 v[8:9], 10, v[8:9]
	v_lshlrev_b64 v[28:29], 10, v[28:29]
	v_lshlrev_b64 v[92:93], 10, v[92:93]
	v_lshlrev_b64 v[98:99], 10, v[98:99]
	v_lshlrev_b64 v[106:107], 10, v[106:107]
	v_lshlrev_b64 v[110:111], 10, v[110:111]
	v_lshl_add_u64 v[6:7], v[40:41], 0, v[4:5]
	v_lshl_add_u64 v[26:27], v[40:41], 0, v[8:9]
	v_lshl_add_u64 v[30:31], v[40:41], 0, v[28:29]
	v_lshl_add_u64 v[94:95], v[40:41], 0, v[92:93]
	v_lshl_add_u64 v[104:105], v[40:41], 0, v[98:99]
	v_lshl_add_u64 v[108:109], v[40:41], 0, v[106:107]
	v_lshl_add_u64 v[112:113], v[40:41], 0, v[110:111]
	global_load_dword v185, v[2:3], off nt
	global_load_dword v186, v[6:7], off nt
	global_load_dword v187, v[26:27], off nt
	global_load_dword v188, v[30:31], off nt
	global_load_dword v189, v[94:95], off nt
	global_load_dword v190, v[104:105], off nt
	global_load_dword v191, v[108:109], off nt
	global_load_dword v192, v[112:113], off nt
	v_lshl_add_u64 v[0:1], v[42:43], 0, v[0:1]
	v_lshl_add_u64 v[2:3], v[42:43], 0, v[4:5]
	v_lshl_add_u64 v[4:5], v[42:43], 0, v[8:9]
	v_lshl_add_u64 v[6:7], v[42:43], 0, v[28:29]
	v_lshl_add_u64 v[8:9], v[42:43], 0, v[92:93]
	v_lshl_add_u64 v[26:27], v[42:43], 0, v[98:99]
	v_lshl_add_u64 v[28:29], v[42:43], 0, v[106:107]
	v_lshl_add_u64 v[30:31], v[42:43], 0, v[110:111]
	global_load_dword v193, v[0:1], off nt
	global_load_dword v194, v[2:3], off nt
	global_load_dword v195, v[4:5], off nt
	global_load_dword v196, v[6:7], off nt
	global_load_dword v197, v[8:9], off nt
	global_load_dword v198, v[26:27], off nt
	global_load_dword v199, v[28:29], off nt
	global_load_dword v200, v[30:31], off nt
	v_or_b32_e32 v0, 32, v34
	v_ashrrev_i32_e32 v1, 31, v0
	v_or_b32_e32 v4, 33, v34
	v_or_b32_e32 v8, 34, v34
	v_or_b32_e32 v28, 35, v34
	v_or_b32_e32 v92, 40, v34
	v_or_b32_e32 v98, 41, v34
	v_or_b32_e32 v106, 42, v34
	v_or_b32_e32 v110, 43, v34
	v_lshlrev_b64 v[0:1], 10, v[0:1]
	v_ashrrev_i32_e32 v5, 31, v4
	v_ashrrev_i32_e32 v9, 31, v8
	v_ashrrev_i32_e32 v29, 31, v28
	v_ashrrev_i32_e32 v93, 31, v92
	v_ashrrev_i32_e32 v99, 31, v98
	v_ashrrev_i32_e32 v107, 31, v106
	v_ashrrev_i32_e32 v111, 31, v110
	v_lshl_add_u64 v[2:3], v[40:41], 0, v[0:1]
	v_lshlrev_b64 v[4:5], 10, v[4:5]
	v_lshlrev_b64 v[8:9], 10, v[8:9]
	v_lshlrev_b64 v[28:29], 10, v[28:29]
	v_lshlrev_b64 v[92:93], 10, v[92:93]
	v_lshlrev_b64 v[98:99], 10, v[98:99]
	v_lshlrev_b64 v[106:107], 10, v[106:107]
	v_lshlrev_b64 v[110:111], 10, v[110:111]
	v_lshl_add_u64 v[6:7], v[40:41], 0, v[4:5]
	v_lshl_add_u64 v[26:27], v[40:41], 0, v[8:9]
	v_lshl_add_u64 v[30:31], v[40:41], 0, v[28:29]
	v_lshl_add_u64 v[94:95], v[40:41], 0, v[92:93]
	v_lshl_add_u64 v[104:105], v[40:41], 0, v[98:99]
	v_lshl_add_u64 v[108:109], v[40:41], 0, v[106:107]
	v_lshl_add_u64 v[112:113], v[40:41], 0, v[110:111]
	global_load_dword v201, v[2:3], off nt
	global_load_dword v202, v[6:7], off nt
	global_load_dword v203, v[26:27], off nt
	global_load_dword v204, v[30:31], off nt
	global_load_dword v205, v[94:95], off nt
	global_load_dword v206, v[104:105], off nt
	global_load_dword v207, v[108:109], off nt
	global_load_dword v208, v[112:113], off nt
	v_lshl_add_u64 v[0:1], v[42:43], 0, v[0:1]
	v_lshl_add_u64 v[2:3], v[42:43], 0, v[4:5]
	v_lshl_add_u64 v[4:5], v[42:43], 0, v[8:9]
	v_lshl_add_u64 v[6:7], v[42:43], 0, v[28:29]
	v_lshl_add_u64 v[8:9], v[42:43], 0, v[92:93]
	v_lshl_add_u64 v[26:27], v[42:43], 0, v[98:99]
	v_lshl_add_u64 v[28:29], v[42:43], 0, v[106:107]
	v_lshl_add_u64 v[30:31], v[42:43], 0, v[110:111]
	global_load_dword v209, v[0:1], off nt
	global_load_dword v221, v[2:3], off nt
	global_load_dword v222, v[4:5], off nt
	global_load_dword v223, v[6:7], off nt
	global_load_dword v224, v[8:9], off nt
	global_load_dword v225, v[26:27], off nt
	global_load_dword v226, v[28:29], off nt
	global_load_dword v227, v[30:31], off nt
	v_or_b32_e32 v0, 48, v34
	v_ashrrev_i32_e32 v1, 31, v0
	v_or_b32_e32 v2, 49, v34
	v_or_b32_e32 v4, 50, v34
	v_or_b32_e32 v6, 51, v34
	v_or_b32_e32 v8, 56, v34
	v_or_b32_e32 v26, 57, v34
	v_or_b32_e32 v28, 58, v34
	v_or_b32_e32 v30, 59, v34
	v_lshlrev_b64 v[108:109], 10, v[0:1]
	v_ashrrev_i32_e32 v3, 31, v2
	v_ashrrev_i32_e32 v5, 31, v4
	v_ashrrev_i32_e32 v7, 31, v6
	v_ashrrev_i32_e32 v9, 31, v8
	v_ashrrev_i32_e32 v27, 31, v26
	v_ashrrev_i32_e32 v29, 31, v28
	v_ashrrev_i32_e32 v31, 31, v30
	v_lshl_add_u64 v[0:1], v[40:41], 0, v[108:109]
	v_lshlrev_b64 v[110:111], 10, v[2:3]
	v_lshlrev_b64 v[112:113], 10, v[4:5]
	v_lshlrev_b64 v[114:115], 10, v[6:7]
	v_lshlrev_b64 v[116:117], 10, v[8:9]
	v_lshlrev_b64 v[118:119], 10, v[26:27]
	v_lshlrev_b64 v[120:121], 10, v[28:29]
	v_lshlrev_b64 v[122:123], 10, v[30:31]
	v_lshl_add_u64 v[2:3], v[40:41], 0, v[110:111]
	v_lshl_add_u64 v[4:5], v[40:41], 0, v[112:113]
	v_lshl_add_u64 v[6:7], v[40:41], 0, v[114:115]
	v_lshl_add_u64 v[8:9], v[40:41], 0, v[116:117]
	v_lshl_add_u64 v[26:27], v[40:41], 0, v[118:119]
	v_lshl_add_u64 v[28:29], v[40:41], 0, v[120:121]
	v_lshl_add_u64 v[30:31], v[40:41], 0, v[122:123]
	global_load_dword v228, v[0:1], off nt
	global_load_dword v229, v[2:3], off nt
	global_load_dword v230, v[4:5], off nt
	global_load_dword v231, v[6:7], off nt
	global_load_dword v232, v[8:9], off nt
	global_load_dword v233, v[26:27], off nt
	global_load_dword v234, v[28:29], off nt
	global_load_dword v235, v[30:31], off nt
	v_fma_f32 v1, v10, s18, -v181
	v_exp_f32_e32 v93, v1
	v_fma_f32 v1, v11, s18, -v181
	v_exp_f32_e32 v94, v1
	v_fma_f32 v1, v12, s18, -v181
	v_exp_f32_e32 v95, v1
	v_fma_f32 v1, v13, s18, -v181
	v_add_f32_e32 v0, v72, v91
	v_exp_f32_e32 v98, v1
	v_add_f32_e32 v0, v93, v0
	v_add_f32_e32 v0, v94, v0
	v_add_f32_e32 v0, v95, v0
	v_add_f32_e32 v8, v98, v0
	v_fma_f32 v0, v14, s18, -v181
	v_exp_f32_e32 v99, v0
	v_fma_f32 v0, v15, s18, -v181
	v_exp_f32_e32 v102, v0
	v_fma_f32 v0, v17, s18, -v181
	v_exp_f32_e32 v91, v0
	v_fma_f32 v0, v16, s18, -v181
	v_exp_f32_e32 v92, v0
	s_waitcnt vmcnt(54)
	v_cvt_pk_bf16_f32 v0, v35, v143
	s_waitcnt vmcnt(52)
	v_cvt_pk_bf16_f32 v1, v144, v145
	s_waitcnt vmcnt(50)
	v_cvt_pk_bf16_f32 v2, v146, v147
	s_waitcnt vmcnt(48)
	v_cvt_pk_bf16_f32 v3, v148, v149
	v_cvt_pk_bf16_f32 v4, v18, v19
	v_cvt_pk_bf16_f32 v5, v20, v21
	v_cvt_pk_bf16_f32 v6, v22, v23
	v_cvt_pk_bf16_f32 v7, v24, v25
	v_add_f32_e32 v8, v99, v8
	v_add_f32_e32 v8, v102, v8
	v_mfma_f32_32x32x16_bf16 v[16:31], v[0:3], v[4:7], 0
	s_waitcnt vmcnt(46)
	v_cvt_pk_bf16_f32 v0, v130, v150
	s_waitcnt vmcnt(44)
	v_cvt_pk_bf16_f32 v1, v151, v152
	s_waitcnt vmcnt(42)
	v_cvt_pk_bf16_f32 v2, v153, v182
	s_waitcnt vmcnt(40)
	v_cvt_pk_bf16_f32 v3, v183, v184
	s_waitcnt vmcnt(38)
	v_cvt_pk_bf16_f32 v104, v185, v186
	s_waitcnt vmcnt(36)
	v_cvt_pk_bf16_f32 v105, v187, v188
	s_waitcnt vmcnt(34)
	v_cvt_pk_bf16_f32 v106, v189, v190
	s_waitcnt vmcnt(32)
	v_cvt_pk_bf16_f32 v107, v191, v192
	v_add_f32_e32 v8, v91, v8
	v_add_f32_e32 v35, v92, v8
	v_mfma_f32_32x32x16_bf16 v[0:15], v[0:3], v[4:7], 0
	v_cvt_pk_bf16_f32 v78, v78, v79
	v_cvt_pk_bf16_f32 v79, v80, v81
	v_cvt_pk_bf16_f32 v80, v82, v83
	v_cvt_pk_bf16_f32 v81, v86, v88
	v_cvt_pk_bf16_f32 v82, v32, v84
	v_cvt_pk_bf16_f32 v83, v85, v87
	v_cvt_pk_bf16_f32 v84, v36, v89
	v_mfma_f32_32x32x16_bf16 v[16:31], v[104:107], v[78:81], v[16:31]
	s_waitcnt vmcnt(30)
	v_cvt_pk_bf16_f32 v104, v193, v194
	s_waitcnt vmcnt(28)
	v_cvt_pk_bf16_f32 v105, v195, v196
	s_waitcnt vmcnt(26)
	v_cvt_pk_bf16_f32 v106, v197, v198
	s_waitcnt vmcnt(24)
	v_cvt_pk_bf16_f32 v107, v199, v200
	s_waitcnt vmcnt(14)
	v_cvt_pk_bf16_f32 v86, v209, v221
	s_waitcnt vmcnt(12)
	v_cvt_pk_bf16_f32 v87, v222, v223
	s_waitcnt vmcnt(10)
	v_cvt_pk_bf16_f32 v88, v224, v225
	v_mfma_f32_32x32x16_bf16 v[0:15], v[104:107], v[78:81], v[0:15]
	v_cvt_pk_bf16_f32 v78, v201, v202
	v_cvt_pk_bf16_f32 v79, v203, v204
	v_cvt_pk_bf16_f32 v80, v205, v206
	v_cvt_pk_bf16_f32 v81, v207, v208
	s_waitcnt vmcnt(8)
	v_cvt_pk_bf16_f32 v89, v226, v227
	v_cvt_pk_bf16_f32 v85, v38, v90
	v_lshl_add_u64 v[104:105], v[42:43], 0, v[118:119]
	v_lshl_add_u64 v[106:107], v[42:43], 0, v[120:121]
	v_mfma_f32_32x32x16_bf16 v[16:31], v[78:81], v[82:85], v[16:31]
	v_lshl_add_u64 v[80:81], v[42:43], 0, v[108:109]
	v_lshl_add_u64 v[108:109], v[42:43], 0, v[122:123]
	v_or_b32_e32 v118, 0x4a, v34
	v_or_b32_e32 v122, 0x4b, v34
	v_ashrrev_i32_e32 v119, 31, v118
	v_ashrrev_i32_e32 v123, 31, v122
	v_lshlrev_b64 v[118:119], 10, v[118:119]
	v_mfma_f32_32x32x16_bf16 v[0:15], v[86:89], v[82:85], v[0:15]
	v_lshl_add_u64 v[82:83], v[42:43], 0, v[110:111]
	v_lshl_add_u64 v[84:85], v[42:43], 0, v[112:113]
	v_lshl_add_u64 v[86:87], v[42:43], 0, v[114:115]
	v_lshl_add_u64 v[88:89], v[42:43], 0, v[116:117]
	global_load_dword v90, v[80:81], off nt
	global_load_dword v130, v[82:83], off nt
	global_load_dword v143, v[84:85], off nt
	global_load_dword v146, v[86:87], off nt
	global_load_dword v147, v[88:89], off nt
	global_load_dword v148, v[104:105], off nt
	global_load_dword v149, v[106:107], off nt
	global_load_dword v150, v[108:109], off nt
	v_or_b32_e32 v80, 64, v34
	v_ashrrev_i32_e32 v81, 31, v80
	v_or_b32_e32 v84, 0x41, v34
	v_or_b32_e32 v88, 0x42, v34
	v_or_b32_e32 v106, 0x43, v34
	v_or_b32_e32 v110, 0x48, v34
	v_or_b32_e32 v114, 0x49, v34
	v_lshlrev_b64 v[80:81], 10, v[80:81]
	v_ashrrev_i32_e32 v85, 31, v84
	v_ashrrev_i32_e32 v89, 31, v88
	v_ashrrev_i32_e32 v107, 31, v106
	v_ashrrev_i32_e32 v111, 31, v110
	v_ashrrev_i32_e32 v115, 31, v114
	v_lshl_add_u64 v[82:83], v[40:41], 0, v[80:81]
	v_lshlrev_b64 v[84:85], 10, v[84:85]
	v_lshlrev_b64 v[88:89], 10, v[88:89]
	v_lshlrev_b64 v[106:107], 10, v[106:107]
	v_lshlrev_b64 v[110:111], 10, v[110:111]
	v_lshlrev_b64 v[114:115], 10, v[114:115]
	v_lshlrev_b64 v[122:123], 10, v[122:123]
	v_lshl_add_u64 v[86:87], v[40:41], 0, v[84:85]
	v_lshl_add_u64 v[104:105], v[40:41], 0, v[88:89]
	v_lshl_add_u64 v[108:109], v[40:41], 0, v[106:107]
	v_lshl_add_u64 v[112:113], v[40:41], 0, v[110:111]
	v_lshl_add_u64 v[116:117], v[40:41], 0, v[114:115]
	v_lshl_add_u64 v[120:121], v[40:41], 0, v[118:119]
	v_lshl_add_u64 v[144:145], v[40:41], 0, v[122:123]
	global_load_dword v151, v[82:83], off nt
	global_load_dword v152, v[86:87], off nt
	global_load_dword v153, v[104:105], off nt
	global_load_dword v182, v[108:109], off nt
	global_load_dword v183, v[112:113], off nt
	global_load_dword v184, v[116:117], off nt
	global_load_dword v185, v[120:121], off nt
	global_load_dword v186, v[144:145], off nt
	v_lshl_add_u64 v[80:81], v[42:43], 0, v[80:81]
	v_lshl_add_u64 v[82:83], v[42:43], 0, v[84:85]
	v_lshl_add_u64 v[84:85], v[42:43], 0, v[88:89]
	v_lshl_add_u64 v[86:87], v[42:43], 0, v[106:107]
	v_lshl_add_u64 v[88:89], v[42:43], 0, v[110:111]
	v_lshl_add_u64 v[104:105], v[42:43], 0, v[114:115]
	v_lshl_add_u64 v[106:107], v[42:43], 0, v[118:119]
	v_lshl_add_u64 v[108:109], v[42:43], 0, v[122:123]
	global_load_dword v187, v[80:81], off nt
	global_load_dword v188, v[82:83], off nt
	global_load_dword v189, v[84:85], off nt
	global_load_dword v190, v[86:87], off nt
	global_load_dword v191, v[88:89], off nt
	global_load_dword v192, v[104:105], off nt
	global_load_dword v193, v[106:107], off nt
	global_load_dword v194, v[108:109], off nt
	v_or_b32_e32 v80, 0x50, v34
	v_ashrrev_i32_e32 v81, 31, v80
	v_or_b32_e32 v84, 0x51, v34
	v_or_b32_e32 v88, 0x52, v34
	v_or_b32_e32 v106, 0x53, v34
	v_or_b32_e32 v110, 0x58, v34
	v_or_b32_e32 v114, 0x59, v34
	v_or_b32_e32 v118, 0x5a, v34
	v_or_b32_e32 v122, 0x5b, v34
	v_lshlrev_b64 v[80:81], 10, v[80:81]
	v_ashrrev_i32_e32 v85, 31, v84
	v_ashrrev_i32_e32 v89, 31, v88
	v_ashrrev_i32_e32 v107, 31, v106
	v_ashrrev_i32_e32 v111, 31, v110
	v_ashrrev_i32_e32 v115, 31, v114
	v_ashrrev_i32_e32 v119, 31, v118
	v_ashrrev_i32_e32 v123, 31, v122
	v_lshl_add_u64 v[82:83], v[40:41], 0, v[80:81]
	v_lshlrev_b64 v[84:85], 10, v[84:85]
	v_lshlrev_b64 v[88:89], 10, v[88:89]
	v_lshlrev_b64 v[106:107], 10, v[106:107]
	v_lshlrev_b64 v[110:111], 10, v[110:111]
	v_lshlrev_b64 v[114:115], 10, v[114:115]
	v_lshlrev_b64 v[118:119], 10, v[118:119]
	v_lshlrev_b64 v[122:123], 10, v[122:123]
	v_lshl_add_u64 v[86:87], v[40:41], 0, v[84:85]
	v_lshl_add_u64 v[104:105], v[40:41], 0, v[88:89]
	v_lshl_add_u64 v[108:109], v[40:41], 0, v[106:107]
	v_lshl_add_u64 v[112:113], v[40:41], 0, v[110:111]
	v_lshl_add_u64 v[116:117], v[40:41], 0, v[114:115]
	v_lshl_add_u64 v[120:121], v[40:41], 0, v[118:119]
	v_lshl_add_u64 v[144:145], v[40:41], 0, v[122:123]
	global_load_dword v195, v[82:83], off nt
	global_load_dword v196, v[86:87], off nt
	global_load_dword v197, v[104:105], off nt
	global_load_dword v198, v[108:109], off nt
	global_load_dword v199, v[112:113], off nt
	global_load_dword v200, v[116:117], off nt
	global_load_dword v201, v[120:121], off nt
	global_load_dword v202, v[144:145], off nt
	v_lshl_add_u64 v[80:81], v[42:43], 0, v[80:81]
	v_lshl_add_u64 v[82:83], v[42:43], 0, v[84:85]
	v_lshl_add_u64 v[84:85], v[42:43], 0, v[88:89]
	v_lshl_add_u64 v[86:87], v[42:43], 0, v[106:107]
	v_lshl_add_u64 v[88:89], v[42:43], 0, v[110:111]
	v_lshl_add_u64 v[104:105], v[42:43], 0, v[114:115]
	v_lshl_add_u64 v[106:107], v[42:43], 0, v[118:119]
	v_lshl_add_u64 v[108:109], v[42:43], 0, v[122:123]
	global_load_dword v203, v[80:81], off nt
	global_load_dword v204, v[82:83], off nt
	global_load_dword v205, v[84:85], off nt
	global_load_dword v206, v[86:87], off nt
	global_load_dword v207, v[88:89], off nt
	global_load_dword v208, v[104:105], off nt
	global_load_dword v209, v[106:107], off nt
	global_load_dword v221, v[108:109], off nt
	v_or_b32_e32 v80, 0x60, v34
	v_or_b32_e32 v122, 0x6b, v34
	v_ashrrev_i32_e32 v81, 31, v80
	v_or_b32_e32 v84, 0x61, v34
	v_or_b32_e32 v88, 0x62, v34
	v_or_b32_e32 v106, 0x63, v34
	v_or_b32_e32 v110, 0x68, v34
	v_or_b32_e32 v114, 0x69, v34
	v_or_b32_e32 v118, 0x6a, v34
	v_ashrrev_i32_e32 v123, 31, v122
	v_fma_f32 v77, v77, s18, -v181
	v_lshlrev_b64 v[80:81], 10, v[80:81]
	v_ashrrev_i32_e32 v85, 31, v84
	v_ashrrev_i32_e32 v89, 31, v88
	v_ashrrev_i32_e32 v107, 31, v106
	v_ashrrev_i32_e32 v111, 31, v110
	v_ashrrev_i32_e32 v115, 31, v114
	v_ashrrev_i32_e32 v119, 31, v118
	v_lshlrev_b64 v[122:123], 10, v[122:123]
	v_exp_f32_e32 v77, v77
	v_fma_f32 v76, v76, s18, -v181
	v_lshl_add_u64 v[82:83], v[40:41], 0, v[80:81]
	v_lshlrev_b64 v[84:85], 10, v[84:85]
	v_lshlrev_b64 v[88:89], 10, v[88:89]
	v_lshlrev_b64 v[106:107], 10, v[106:107]
	v_lshlrev_b64 v[110:111], 10, v[110:111]
	v_lshlrev_b64 v[114:115], 10, v[114:115]
	v_lshlrev_b64 v[118:119], 10, v[118:119]
	v_lshl_add_u64 v[144:145], v[40:41], 0, v[122:123]
	v_exp_f32_e32 v76, v76
	s_waitcnt vmcnt(46)
	v_cvt_pk_bf16_f32 v36, v228, v229
	v_lshl_add_u64 v[86:87], v[40:41], 0, v[84:85]
	v_lshl_add_u64 v[104:105], v[40:41], 0, v[88:89]
	v_lshl_add_u64 v[108:109], v[40:41], 0, v[106:107]
	v_lshl_add_u64 v[112:113], v[40:41], 0, v[110:111]
	v_lshl_add_u64 v[116:117], v[40:41], 0, v[114:115]
	v_lshl_add_u64 v[120:121], v[40:41], 0, v[118:119]
	global_load_dword v222, v[82:83], off nt
	global_load_dword v223, v[86:87], off nt
	global_load_dword v224, v[104:105], off nt
	global_load_dword v225, v[108:109], off nt
	global_load_dword v226, v[112:113], off nt
	global_load_dword v227, v[116:117], off nt
	global_load_dword v228, v[120:121], off nt
	s_nop 0
	global_load_dword v144, v[144:145], off nt
	v_add_f32_e32 v32, v77, v35
	v_add_f32_e32 v79, v76, v32
	v_fma_f32 v32, s17, v180, -v181
	v_lshl_add_u64 v[80:81], v[42:43], 0, v[80:81]
	v_exp_f32_e32 v78, v32
	v_cvt_pk_bf16_f32 v32, v37, v39
	s_waitcnt vmcnt(52)
	v_cvt_pk_bf16_f32 v37, v230, v231
	s_waitcnt vmcnt(50)
	v_cvt_pk_bf16_f32 v38, v232, v233
	v_lshl_add_u64 v[82:83], v[42:43], 0, v[84:85]
	v_lshl_add_u64 v[84:85], v[42:43], 0, v[88:89]
	v_lshl_add_u64 v[86:87], v[42:43], 0, v[106:107]
	v_lshl_add_u64 v[88:89], v[42:43], 0, v[110:111]
	v_lshl_add_u64 v[104:105], v[42:43], 0, v[114:115]
	v_lshl_add_u64 v[106:107], v[42:43], 0, v[118:119]
	v_lshl_add_u64 v[108:109], v[42:43], 0, v[122:123]
	global_load_dword v122, v[80:81], off nt
	global_load_dword v123, v[82:83], off nt
	global_load_dword v145, v[84:85], off nt
	global_load_dword v229, v[86:87], off nt
	global_load_dword v230, v[88:89], off nt
	global_load_dword v231, v[104:105], off nt
	global_load_dword v232, v[106:107], off nt
	global_load_dword v233, v[108:109], off nt
	v_or_b32_e32 v80, 0x70, v34
	v_or_b32_e32 v106, 0x73, v34
	v_or_b32_e32 v110, 0x78, v34
	v_or_b32_e32 v114, 0x79, v34
	v_ashrrev_i32_e32 v81, 31, v80
	v_or_b32_e32 v84, 0x71, v34
	v_or_b32_e32 v88, 0x72, v34
	v_ashrrev_i32_e32 v107, 31, v106
	v_ashrrev_i32_e32 v111, 31, v110
	v_ashrrev_i32_e32 v115, 31, v114
	v_or_b32_e32 v118, 0x7a, v34
	v_or_b32_e32 v34, 0x7b, v34
	v_lshlrev_b64 v[80:81], 10, v[80:81]
	v_ashrrev_i32_e32 v85, 31, v84
	v_ashrrev_i32_e32 v89, 31, v88
	v_lshlrev_b64 v[106:107], 10, v[106:107]
	v_lshlrev_b64 v[110:111], 10, v[110:111]
	v_lshlrev_b64 v[114:115], 10, v[114:115]
	v_ashrrev_i32_e32 v119, 31, v118
	v_ashrrev_i32_e32 v35, 31, v34
	v_lshl_add_u64 v[82:83], v[40:41], 0, v[80:81]
	v_lshlrev_b64 v[84:85], 10, v[84:85]
	v_lshlrev_b64 v[88:89], 10, v[88:89]
	v_lshl_add_u64 v[108:109], v[40:41], 0, v[106:107]
	v_lshl_add_u64 v[112:113], v[40:41], 0, v[110:111]
	v_lshl_add_u64 v[116:117], v[40:41], 0, v[114:115]
	v_lshlrev_b64 v[118:119], 10, v[118:119]
	v_lshlrev_b64 v[34:35], 10, v[34:35]
	s_waitcnt vmcnt(56)
	v_cvt_pk_bf16_f32 v39, v234, v235
	v_lshl_add_u64 v[86:87], v[40:41], 0, v[84:85]
	v_lshl_add_u64 v[104:105], v[40:41], 0, v[88:89]
	v_lshl_add_u64 v[120:121], v[40:41], 0, v[118:119]
	v_lshl_add_u64 v[40:41], v[40:41], 0, v[34:35]
	global_load_dword v234, v[82:83], off nt
	global_load_dword v235, v[86:87], off nt
	global_load_dword v236, v[104:105], off nt
	s_nop 0
	global_load_dword v108, v[108:109], off nt
	s_nop 0
	global_load_dword v109, v[112:113], off nt
	s_nop 0
	global_load_dword v112, v[116:117], off nt
	global_load_dword v113, v[120:121], off nt
	s_nop 0
	global_load_dword v116, v[40:41], off nt
	v_lshl_add_u64 v[40:41], v[42:43], 0, v[80:81]
	v_lshl_add_u64 v[80:81], v[42:43], 0, v[84:85]
	v_lshl_add_u64 v[82:83], v[42:43], 0, v[88:89]
	v_lshl_add_u64 v[84:85], v[42:43], 0, v[106:107]
	v_lshl_add_u64 v[86:87], v[42:43], 0, v[110:111]
	v_lshl_add_u64 v[88:89], v[42:43], 0, v[114:115]
	v_lshl_add_u64 v[104:105], v[42:43], 0, v[118:119]
	v_lshl_add_u64 v[34:35], v[42:43], 0, v[34:35]
	global_load_dword v40, v[40:41], off nt
	s_nop 0
	global_load_dword v41, v[80:81], off nt
	global_load_dword v42, v[82:83], off nt
	global_load_dword v43, v[84:85], off nt
	s_nop 0
	global_load_dword v80, v[86:87], off nt
	global_load_dword v81, v[88:89], off nt
	global_load_dword v82, v[104:105], off nt
	global_load_dword v83, v[34:35], off nt
	v_cvt_pk_bf16_f32 v33, v33, v64
	v_cvt_pk_bf16_f32 v34, v65, v66
	v_cvt_pk_bf16_f32 v35, v67, v69
	v_add_f32_e32 v64, v78, v79
	v_add_f32_e32 v64, v78, v64
	v_mfma_f32_32x32x16_bf16 v[16:31], v[36:39], v[32:35], v[16:31]
	s_waitcnt vmcnt(62)
	v_cvt_pk_bf16_f32 v36, v90, v130
	v_cvt_pk_bf16_f32 v37, v143, v146
	v_cvt_pk_bf16_f32 v38, v147, v148
	v_cvt_pk_bf16_f32 v39, v149, v150
	v_add_f32_e32 v64, v78, v64
	v_add_f32_e32 v64, v78, v64
	s_ashr_i32 s95, s94, 31
	v_mfma_f32_32x32x16_bf16 v[0:15], v[36:39], v[32:35], v[0:15]
	v_cvt_pk_bf16_f32 v32, v151, v152
	s_waitcnt vmcnt(60)
	v_cvt_pk_bf16_f32 v33, v153, v182
	s_waitcnt vmcnt(58)
	v_cvt_pk_bf16_f32 v34, v183, v184
	s_waitcnt vmcnt(56)
	v_cvt_pk_bf16_f32 v35, v185, v186
	v_cvt_pk_bf16_f32 v36, v44, v45
	v_cvt_pk_bf16_f32 v37, v46, v47
	v_cvt_pk_bf16_f32 v38, v49, v51
	v_cvt_pk_bf16_f32 v39, v53, v55
	v_add_f32_e32 v44, v78, v64
	v_add_f32_e32 v44, v78, v44
	v_mfma_f32_32x32x16_bf16 v[16:31], v[32:35], v[36:39], v[16:31]
	s_waitcnt vmcnt(54)
	v_cvt_pk_bf16_f32 v32, v187, v188
	s_waitcnt vmcnt(52)
	v_cvt_pk_bf16_f32 v33, v189, v190
	s_waitcnt vmcnt(50)
	v_cvt_pk_bf16_f32 v34, v191, v192
	s_waitcnt vmcnt(48)
	v_cvt_pk_bf16_f32 v35, v193, v194
	v_add_f32_e32 v44, v78, v44
	v_add_f32_e32 v44, v78, v44
	v_add_f32_e32 v44, v78, v44
	v_mfma_f32_32x32x16_bf16 v[0:15], v[32:35], v[36:39], v[0:15]
	s_waitcnt vmcnt(46)
	v_cvt_pk_bf16_f32 v32, v195, v196
	s_waitcnt vmcnt(44)
	v_cvt_pk_bf16_f32 v33, v197, v198
	s_waitcnt vmcnt(42)
	v_cvt_pk_bf16_f32 v34, v199, v200
	s_waitcnt vmcnt(40)
	v_cvt_pk_bf16_f32 v35, v201, v202
	v_cvt_pk_bf16_f32 v36, v48, v50
	v_cvt_pk_bf16_f32 v37, v52, v54
	v_cvt_pk_bf16_f32 v38, v57, v59
	v_cvt_pk_bf16_f32 v39, v61, v70
	v_add_f32_e32 v44, v78, v44
	v_add_f32_e32 v44, v78, v44
	v_mfma_f32_32x32x16_bf16 v[16:31], v[32:35], v[36:39], v[16:31]
	s_waitcnt vmcnt(38)
	v_cvt_pk_bf16_f32 v32, v203, v204
	s_waitcnt vmcnt(36)
	v_cvt_pk_bf16_f32 v33, v205, v206
	s_waitcnt vmcnt(34)
	v_cvt_pk_bf16_f32 v34, v207, v208
	s_waitcnt vmcnt(32)
	v_cvt_pk_bf16_f32 v35, v209, v221
	v_add_f32_e32 v183, v78, v44
	ds_bpermute_b32 v184, v68, v183
	s_lshl_b64 s[24:25], s[94:95], 9
	v_mfma_f32_32x32x16_bf16 v[0:15], v[32:35], v[36:39], v[0:15]
	s_waitcnt vmcnt(30)
	v_cvt_pk_bf16_f32 v32, v222, v223
	s_waitcnt vmcnt(28)
	v_cvt_pk_bf16_f32 v33, v224, v225
	s_waitcnt vmcnt(26)
	v_cvt_pk_bf16_f32 v34, v226, v227
	s_waitcnt vmcnt(24)
	v_cvt_pk_bf16_f32 v35, v228, v144
	v_cvt_pk_bf16_f32 v36, v56, v58
	v_cvt_pk_bf16_f32 v37, v60, v63
	v_cvt_pk_bf16_f32 v38, v71, v73
	v_cvt_pk_bf16_f32 v39, v74, v75
	s_add_u32 s13, s56, s24
	s_addc_u32 s15, s57, s25
	v_mfma_f32_32x32x16_bf16 v[16:31], v[32:35], v[36:39], v[16:31]
	s_waitcnt vmcnt(22)
	v_cvt_pk_bf16_f32 v32, v122, v123
	s_waitcnt vmcnt(20)
	v_cvt_pk_bf16_f32 v33, v145, v229
	s_waitcnt vmcnt(18)
	v_cvt_pk_bf16_f32 v34, v230, v231
	s_waitcnt vmcnt(16)
	v_cvt_pk_bf16_f32 v35, v232, v233
	s_lshl_b32 s14, s14, 1
	s_add_u32 s94, s13, s14
	s_addc_u32 s95, s15, 0
	v_mov_b32_e32 v54, 0
	v_mov_b32_e32 v55, 0
	s_and_saveexec_b64 s[14:15], s[4:5]
	v_lshlrev_b32_e32 v44, 1, v136
	v_lshlrev_b32_e32 v45, 1, v124
	s_nop 1
	global_load_ushort v46, v44, s[94:95]
	global_load_ushort v47, v44, s[94:95] offset:512
	global_load_ushort v48, v44, s[94:95] offset:1024
	global_load_ushort v49, v44, s[94:95] offset:1536
	global_load_ushort v50, v45, s[94:95]
	global_load_ushort v51, v45, s[94:95] offset:512
	global_load_ushort v52, v45, s[94:95] offset:1024
	global_load_ushort v53, v45, s[94:95] offset:1536
	s_mov_b64 exec, s[14:15]
	v_mfma_f32_32x32x16_bf16 v[0:15], v[32:35], v[36:39], v[0:15]
	s_waitcnt vmcnt(22)
	v_cvt_pk_bf16_f32 v32, v234, v235
	s_waitcnt vmcnt(20)
	v_cvt_pk_bf16_f32 v33, v236, v108
	s_waitcnt vmcnt(18)
	v_cvt_pk_bf16_f32 v34, v109, v112
	s_waitcnt vmcnt(16)
	v_cvt_pk_bf16_f32 v35, v113, v116
	v_cvt_pk_bf16_f32 v36, v62, v72
	v_cvt_pk_bf16_f32 v37, v93, v94
	v_cvt_pk_bf16_f32 v38, v95, v98
	v_cvt_pk_bf16_f32 v39, v99, v102
	v_readlane_b32 s69, v254, 19
	v_readlane_b32 s70, v254, 20
	v_mfma_f32_32x32x16_bf16 v[16:31], v[32:35], v[36:39], v[16:31]
	s_waitcnt vmcnt(14)
	v_cvt_pk_bf16_f32 v32, v40, v41
	s_waitcnt vmcnt(12)
	v_cvt_pk_bf16_f32 v33, v42, v43
	s_waitcnt vmcnt(10)
	v_cvt_pk_bf16_f32 v34, v80, v81
	s_waitcnt vmcnt(8)
	v_cvt_pk_bf16_f32 v35, v82, v83
	v_readlane_b32 s71, v254, 21
	s_nop 0
	v_mfma_f32_32x32x16_bf16 v[0:15], v[32:35], v[36:39], v[0:15]
	v_mov_b32_e32 v34, 0
	v_mov_b32_e32 v32, 0
	v_mov_b32_e32 v33, 0
	s_waitcnt vmcnt(0)
	s_and_saveexec_b64 vcc, s[4:5]

	v_lshl_or_b32 v32, v47, 16, v46
	v_lshl_or_b32 v33, v49, 16, v48
	v_lshl_or_b32 v54, v51, 16, v50
	v_lshl_or_b32 v55, v53, 16, v52


.LBB0_742:
	s_or_b64 exec, exec, vcc
	v_mov_b32_e32 v35, v34
	v_cvt_pk_bf16_f32 v38, v78, v78
	v_cvt_pk_bf16_f32 v36, v91, v92
	v_cvt_pk_bf16_f32 v37, v77, v76
	v_mov_b32_e32 v39, v38
	s_nop 1
	v_mfma_f32_32x32x16_bf16 v[16:31], v[32:35], v[36:39], v[16:31]
	v_mov_b32_e32 v32, v54
	v_mov_b32_e32 v33, v55


.LBB0_744:

	v_mov_b32_e32 v35, v34
	s_mov_b32 s93, s92
	s_mov_b32 s94, s92
	s_mov_b32 s95, s92
	v_lshlrev_b32_e32 v40, 6, v103
	v_mfma_f32_32x32x16_bf16 v[0:15], v[32:35], v[36:39], v[0:15]
	v_mov_b64_e32 v[32:33], s[92:93]
	v_mov_b64_e32 v[34:35], s[94:95]
	v_mov_b32_e32 v36, v38
	v_mov_b32_e32 v37, v38
	v_mov_b32_e32 v39, v38
	v_or_b32_e32 v182, v40, v137
	v_lshlrev_b64 v[102:103], 11, v[96:97]
	v_mfma_f32_32x32x16_bf16 v[16:31], v[32:35], v[36:39], v[16:31]
	s_ashr_i32 s13, s12, 31
	v_readlane_b32 s56, v254, 6
	s_lshl_b64 s[12:13], s[12:13], 14
	v_readlane_b32 s64, v254, 14
	v_readlane_b32 s65, v254, 15
	s_add_u32 s94, s64, s12
	s_addc_u32 s95, s65, s13
	v_mfma_f32_32x32x16_bf16 v[0:15], v[32:35], v[36:39], v[0:15]
	v_or_b32_e32 v32, v102, v182
	v_mov_b32_e32 v33, v103
	v_lshlrev_b64 v[32:33], 1, v[32:33]
	v_lshl_add_u64 v[34:35], s[40:41], 0, v[32:33]
	v_lshl_add_u64 v[40:41], s[0:1], 0, v[32:33]
	global_load_dwordx2 v[108:109], v[34:35], off
	global_load_dwordx2 v[112:113], v[40:41], off
	v_lshl_add_u64 v[34:35], s[90:91], 0, v[32:33]
	global_load_dwordx2 v[110:111], v[34:35], off
	s_add_u32 s12, s94, 0x2000
	s_addc_u32 s13, s95, 0
	v_readlane_b32 s57, v254, 7
	v_readlane_b32 s58, v254, 8
	v_readlane_b32 s59, v254, 9
	v_readlane_b32 s60, v254, 10
	v_readlane_b32 s61, v254, 11
	v_readlane_b32 s62, v254, 12
	v_readlane_b32 s63, v254, 13
	v_readlane_b32 s66, v254, 16
	v_readlane_b32 s67, v254, 17
	v_readlane_b32 s68, v254, 18
	v_readlane_b32 s69, v254, 19
	v_readlane_b32 s70, v254, 20
	v_readlane_b32 s71, v254, 21
	s_and_saveexec_b64 s[14:15], s[52:53]
	s_xor_b64 vcc, exec, s[14:15]
	s_cbranch_execz .LBB0_746
	global_load_dwordx2 v[222:223], v[40:41], off offset:-4096


